# forget-weight table fill with all 16 loads in flight (was serialized pairs) + row loads hoisted in the last-layer final residual/norm variant; bit-identical
# baseline (speedup 1.0000x reference)
; #define LAS __attribute__((address_space(3)))
; __device__ __forceinline__ void ew_phase(const Frame& F, const bf16_t* f, const float* gpost, float alpha, const float* hin, float* hout, const float* gpre, bf16_t* xn, ...
;     LAS float* WF = (LAS float*)(F.lds + 131072 - 32768);
;     if (win_l) {
;         for (int e = F.tid; e < DM * 8; e += 512) WF[(e & 7) * DM + (e >> 3)] = win_l[(size_t)(e >> 3) * INW + 3072 + (e & 7)];
;         asm volatile("s_waitcnt lgkmcnt(0)" ::: "memory"); __syncthreads();
.LBB0_192:
	s_or_b64 exec, exec, s[8:9]
	v_readlane_b32 s2, v254, 60
	v_mov_b32_e32 v42, v224
	s_lshl_b32 s8, s2, 3
	s_barrier
	s_nop 0
	v_readfirstlane_b32 s2, v42
	s_ashr_i32 s21, s2, 6
	v_readlane_b32 s2, v251, 39
	s_add_i32 s20, s21, s2
	v_readlane_b32 s2, v252, 6
	v_readlane_b32 s3, v252, 7
	v_and_b32_e32 v98, 63, v42
	s_and_b64 vcc, exec, s[2:3]
	s_cbranch_vccz .LBB0_212
	s_mov_b64 s[10:11], -1
	s_and_b64 vcc, exec, s[0:1]
	s_cbranch_vccz .LBB0_214
	s_movk_i32 s0, 0x2000
	v_cmp_gt_i32_e32 vcc, s0, v42
	v_and_b32_e32 v48, 7, v42
	s_and_saveexec_b64 s[0:1], vcc
	s_cbranch_execz .LBB0_206
	v_readlane_b32 s2, v254, 60
	s_mov_b32 s3, s73
	s_mul_i32 s2, s2, 0x382000
	v_readlane_b32 s36, v251, 7
	v_max_i32_e32 v0, 0x1e00, v42
	s_lshl_b64 s[2:3], s[2:3], 2
	v_readlane_b32 s38, v251, 9
	v_sub_u32_e32 v0, v0, v42
	v_readlane_b32 s39, v251, 10
	s_add_u32 s10, s38, s2
	v_add_u32_e32 v0, 0x1ff, v0
	s_movk_i32 s2, 0x1ff
	s_addc_u32 s11, s39, s3
	v_lshl_add_u32 v4, v48, 12, s29
	v_cmp_lt_u32_e32 vcc, s2, v0
	s_mov_b64 s[14:15], -1
	v_mov_b32_e32 v2, v42
	v_readlane_b32 s37, v251, 8
	v_readlane_b32 s40, v251, 11
	v_readlane_b32 s41, v251, 12
	v_readlane_b32 s42, v251, 13
	v_readlane_b32 s43, v251, 14
	v_readlane_b32 s44, v251, 15
	v_readlane_b32 s45, v251, 16
	v_readlane_b32 s46, v251, 17
	v_readlane_b32 s47, v251, 18
	v_readlane_b32 s48, v251, 19
	v_readlane_b32 s49, v251, 20
	v_readlane_b32 s50, v251, 21
	v_readlane_b32 s51, v251, 22
	v_lshrrev_b32_e32 v2, 3, v42
	v_mul_u32_u24_e32 v3, 0x3820, v2
	v_lshl_add_u32 v3, v48, 2, v3
	v_add_u32_e32 v3, 0x3000, v3
	v_lshl_add_u32 v2, v2, 2, v4
	s_mov_b64 s[12:13], s[10:11]
	global_load_dword v50, v3, s[12:13]
	s_add_u32 s12, s12, 0xe0800
	s_addc_u32 s13, s13, 0
	global_load_dword v51, v3, s[12:13]
	s_add_u32 s12, s12, 0xe0800
	s_addc_u32 s13, s13, 0
	global_load_dword v52, v3, s[12:13]
	s_add_u32 s12, s12, 0xe0800
	s_addc_u32 s13, s13, 0
	global_load_dword v53, v3, s[12:13]
	s_add_u32 s12, s12, 0xe0800
	s_addc_u32 s13, s13, 0
	global_load_dword v54, v3, s[12:13]
	s_add_u32 s12, s12, 0xe0800
	s_addc_u32 s13, s13, 0
	global_load_dword v55, v3, s[12:13]
	s_add_u32 s12, s12, 0xe0800
	s_addc_u32 s13, s13, 0
	global_load_dword v56, v3, s[12:13]
	s_add_u32 s12, s12, 0xe0800
	s_addc_u32 s13, s13, 0
	global_load_dword v57, v3, s[12:13]
	s_add_u32 s12, s12, 0xe0800
	s_addc_u32 s13, s13, 0
	global_load_dword v58, v3, s[12:13]
	s_add_u32 s12, s12, 0xe0800
	s_addc_u32 s13, s13, 0
	global_load_dword v59, v3, s[12:13]
	s_add_u32 s12, s12, 0xe0800
	s_addc_u32 s13, s13, 0
	global_load_dword v60, v3, s[12:13]
	s_add_u32 s12, s12, 0xe0800
	s_addc_u32 s13, s13, 0
	global_load_dword v61, v3, s[12:13]
	s_add_u32 s12, s12, 0xe0800
	s_addc_u32 s13, s13, 0
	global_load_dword v62, v3, s[12:13]
	s_add_u32 s12, s12, 0xe0800
	s_addc_u32 s13, s13, 0
	global_load_dword v63, v3, s[12:13]
	s_add_u32 s12, s12, 0xe0800
	s_addc_u32 s13, s13, 0
	global_load_dword v64, v3, s[12:13]
	s_add_u32 s12, s12, 0xe0800
	s_addc_u32 s13, s13, 0
	global_load_dword v65, v3, s[12:13]
	s_waitcnt vmcnt(15)
	ds_write_b32 v2, v50
	s_waitcnt vmcnt(14)
	ds_write_b32 v2, v51 offset:256
	s_waitcnt vmcnt(13)
	ds_write_b32 v2, v52 offset:512
	s_waitcnt vmcnt(12)
	ds_write_b32 v2, v53 offset:768
	s_waitcnt vmcnt(11)
	ds_write_b32 v2, v54 offset:1024
	s_waitcnt vmcnt(10)
	ds_write_b32 v2, v55 offset:1280
	s_waitcnt vmcnt(9)
	ds_write_b32 v2, v56 offset:1536
	s_waitcnt vmcnt(8)
	ds_write_b32 v2, v57 offset:1792
	s_waitcnt vmcnt(7)
	ds_write_b32 v2, v58 offset:2048
	s_waitcnt vmcnt(6)
	ds_write_b32 v2, v59 offset:2304
	s_waitcnt vmcnt(5)
	ds_write_b32 v2, v60 offset:2560
	s_waitcnt vmcnt(4)
	ds_write_b32 v2, v61 offset:2816
	s_waitcnt vmcnt(3)
	ds_write_b32 v2, v62 offset:3072
	s_waitcnt vmcnt(2)
	ds_write_b32 v2, v63 offset:3328
	s_waitcnt vmcnt(1)
	ds_write_b32 v2, v64 offset:3584
	s_waitcnt vmcnt(0)
	ds_write_b32 v2, v65 offset:3840

; __device__ __forceinline__ float bf_lo(unsigned w) { return __uint_as_float(w << 16); }
; __device__ __forceinline__ float bf_hi(unsigned w) { return __uint_as_float(w & 0xffff0000u); }
; __device__ __forceinline__ void ew_phase(const Frame& F, const bf16_t* f, const float* gpost, float alpha, const float* hin, float* hout, const float* gpre, bf16_t* xn, ...
;     ...
;     for (int it_ = 0; it_ < it_n; ++it_) {
;         const int m = prow0 >= 0 ? prow0 + F.wave * 8 + it_ : F.gw + it_ * F.NGW; if (m >= T) break;
;         const u32x2* fr = (const u32x2*)(f + (size_t)m * DM) + F.lane; const f32x4* hr = (const f32x4*)(hin + (size_t)m * DM) + F.lane;
;         f32x4 fv[4], hv[4]; float s = 0.f;
; #pragma unroll
;         for (int j = 0; j < 4; ++j) { const u32x2 w = fr[64 * j]; hv[j] = in24 ? load24(h24 + (size_t)m * (DM * 3), F.lane + 64 * j) : hr[64 * j]; fv[j] = (f32x4){bf_lo(w.x), bf_hi(w.x), bf_lo(w.y), bf_hi(w.y)};
;             s += (fv[j].x * fv[j].x + fv[j].y * fv[j].y) + (fv[j].z * fv[j].z + fv[j].w * fv[j].w); }
;         const float rstd = alpha / sqrtf(wave_sum(s) * (1.f / DM) + RMS_EPS);
;         float s2 = 0.f; f32x4* ho = (f32x4*)(hout + (size_t)m * DM) + F.lane;
; #pragma unroll
;         for (int j = 0; j < 4; ++j) { hv[j] = hv[j] + fv[j] * rstd * gp[j]; if (out24) store24(h24 + (size_t)m * (DM * 3), F.lane + 64 * j, hv[j]); else ho[64 * j] = hv[j]; s2 += (hv[j].x * hv[j].x + hv[j].y * hv[j].y) + (hv[j].z * hv[j].z + hv[j].w * hv[j].w); }
.LBB0_911:
	v_readlane_b32 s0, v252, 11
	s_add_i32 s6, s2, s3
	v_readlane_b32 s1, v252, 12
	s_and_b64 s[0:1], s[0:1], exec
	s_cselect_b32 s6, s6, s8
	s_cmpk_gt_i32 s6, 0x3fff
	s_mov_b64 s[0:1], -1
	s_cbranch_scc1 .LBB0_910
	s_ashr_i32 s7, s6, 31
	s_lshl_b64 s[0:1], s[6:7], 11
	v_lshl_add_u64 v[56:57], v[18:19], 0, s[0:1]
	s_mul_i32 s0, s6, 0xc00
	s_mul_hi_i32 s1, s6, 0xc00
	s_add_u32 s0, s13, s0
	s_addc_u32 s1, s14, s1
	s_waitcnt vmcnt(6)
	v_lshl_add_u64 v[22:23], s[0:1], 0, v[36:37]
	v_lshl_add_u64 v[30:31], s[0:1], 0, v[38:39]
	v_lshl_add_u64 v[162:163], s[0:1], 0, v[40:41]
	v_lshl_add_u64 v[164:165], s[0:1], 0, v[42:43]
	global_load_dwordx2 v[28:29], v[56:57], off
	global_load_dwordx2 v[24:25], v[22:23], off
	global_load_dwordx2 v[26:27], v[22:23], off offset:4
	global_load_dwordx2 v[44:45], v[56:57], off offset:512
	global_load_dwordx2 v[32:33], v[30:31], off
	global_load_dwordx2 v[46:47], v[30:31], off offset:4
	global_load_dwordx2 v[54:55], v[56:57], off offset:1024
	global_load_dwordx2 v[50:51], v[162:163], off
	global_load_dwordx2 v[52:53], v[162:163], off offset:4
	global_load_dwordx2 v[60:61], v[56:57], off offset:1536
	global_load_dwordx2 v[58:59], v[164:165], off
	global_load_dwordx2 v[62:63], v[164:165], off offset:4
	s_mov_b32 s9, 0xff00
	s_add_i32 s3, s3, 1
	s_addk_i32 s8, 0x800
	s_waitcnt vmcnt(10)
	v_lshrrev_b32_e32 v25, 8, v25
	s_waitcnt vmcnt(9)
	v_lshlrev_b32_e32 v0, 24, v27
	v_lshlrev_b32_e32 v23, 16, v26
	v_and_b32_e32 v25, 0xffff00, v25
	v_and_b32_sdwa v26, v24, s9 dst_sel:DWORD dst_unused:UNUSED_PAD src0_sel:WORD_1 src1_sel:DWORD
	v_lshlrev_b32_e32 v22, 8, v24
	v_or_b32_e32 v24, v0, v25
	v_or_b32_e32 v23, v23, v26
	v_and_b32_e32 v25, 0xffffff00, v27
	v_lshlrev_b32_e32 v26, 16, v28
	v_and_b32_e32 v27, 0xffff0000, v28
	v_lshlrev_b32_e32 v28, 16, v29
	v_and_b32_e32 v29, 0xffff0000, v29
	v_mul_f32_e32 v0, v29, v29
	s_waitcnt vmcnt(7)
	v_lshrrev_b32_e32 v33, 8, v33
	v_pk_fma_f32 v[66:67], v[28:29], v[28:29], v[0:1] op_sel_hi:[1,1,0]
	s_waitcnt vmcnt(6)
	v_lshlrev_b32_e32 v0, 24, v47
	v_and_b32_e32 v33, 0xffff00, v33
	v_lshlrev_b32_e32 v30, 8, v32
	v_lshlrev_b32_e32 v31, 16, v46
	v_and_b32_sdwa v35, v32, s9 dst_sel:DWORD dst_unused:UNUSED_PAD src0_sel:WORD_1 src1_sel:DWORD
	v_or_b32_e32 v32, v0, v33
	v_and_b32_e32 v33, 0xffffff00, v47
	v_lshlrev_b32_e32 v47, 16, v45
	v_lshlrev_b32_e32 v46, 16, v44
	v_and_b32_e32 v45, 0xffff0000, v45
	v_and_b32_e32 v44, 0xffff0000, v44
	v_pk_mul_f32 v[48:49], v[44:45], v[44:45]
	v_or_b32_e32 v31, v31, v35
	v_pk_fma_f32 v[68:69], v[46:47], v[46:47], v[48:49]
	v_lshl_add_u64 v[48:49], s[0:1], 0, v[40:41]
	v_lshl_add_u64 v[56:57], s[0:1], 0, v[42:43]
	v_mov_b32_e32 v72, v66
	v_pk_add_f32 v[68:69], v[68:69], v[68:69] op_sel:[0,1] op_sel_hi:[1,0]
	s_waitcnt vmcnt(4)
	v_lshrrev_b32_e32 v49, 8, v51
	s_waitcnt vmcnt(3)
	v_lshlrev_b32_e32 v0, 24, v53
	v_and_b32_e32 v49, 0xffff00, v49
	s_waitcnt vmcnt(1)
	v_lshrrev_b32_e32 v57, 8, v59
	v_lshlrev_b32_e32 v48, 8, v50
	v_and_b32_sdwa v51, v50, s9 dst_sel:DWORD dst_unused:UNUSED_PAD src0_sel:WORD_1 src1_sel:DWORD
	v_or_b32_e32 v50, v0, v49
	s_waitcnt vmcnt(0)
	v_lshlrev_b32_e32 v0, 24, v63
	v_and_b32_e32 v57, 0xffff00, v57
	v_lshlrev_b32_e32 v35, 16, v52
	v_lshlrev_b32_e32 v56, 8, v58
	v_and_b32_sdwa v59, v58, s9 dst_sel:DWORD dst_unused:UNUSED_PAD src0_sel:WORD_1 src1_sel:DWORD
	v_or_b32_e32 v58, v0, v57
	v_mul_f32_e32 v0, v27, v27
	v_or_b32_e32 v49, v35, v51
	v_lshlrev_b32_e32 v35, 16, v62
	v_lshlrev_b32_e32 v65, 16, v60
	v_pk_fma_f32 v[70:71], v[26:27], v[26:27], v[0:1] op_sel_hi:[1,1,0]
	v_or_b32_e32 v57, v35, v59
	v_and_b32_e32 v59, 0xffffff00, v63
	v_and_b32_e32 v63, 0xffff0000, v60
	v_mov_b32_e32 v64, v70
	v_mov_b32_e32 v73, v65
	v_and_b32_e32 v51, 0xffffff00, v53
	v_and_b32_e32 v53, 0xffff0000, v54
	v_mul_f32_e32 v35, v63, v63
	v_pk_add_f32 v[66:67], v[70:71], v[66:67]
	v_pk_mul_f32 v[70:71], v[64:65], v[72:73]
	v_lshlrev_b32_e32 v52, 16, v54
	v_lshlrev_b32_e32 v54, 16, v55
	v_and_b32_e32 v55, 0xffff0000, v55
	v_mov_b32_e32 v67, v71
	v_mov_b32_e32 v69, v35
	v_mul_f32_e32 v0, v53, v53
	v_lshlrev_b32_e32 v60, 16, v61
	v_and_b32_e32 v61, 0xffff0000, v61
	v_pk_add_f32 v[66:67], v[66:67], v[68:69]
	v_pk_fma_f32 v[68:69], v[52:53], v[52:53], v[0:1] op_sel_hi:[1,1,0]
	v_mul_f32_e32 v0, v55, v55
	v_mul_f32_e32 v62, v60, v60
	v_mul_f32_e32 v74, v61, v61
	v_pk_fma_f32 v[70:71], v[54:55], v[54:55], v[0:1] op_sel_hi:[1,1,0]
	v_and_b32_e32 v35, 64, v230
	v_mov_b32_e32 v69, v62
	v_mov_b32_e32 v71, v74
	v_add_u32_e32 v35, 64, v35
	v_xor_b32_e32 v62, 1, v230
	v_pk_add_f32 v[68:69], v[68:69], v[70:71]
	v_cmp_lt_i32_e32 vcc, v62, v35
	v_pk_add_f32 v[66:67], v[66:67], v[68:69]
	s_nop 0
	v_cndmask_b32_e32 v62, v230, v62, vcc
	v_add_f32_e32 v0, v66, v67
	v_lshlrev_b32_e32 v62, 2, v62
	ds_bpermute_b32 v62, v62, v0
	s_waitcnt lgkmcnt(0)
; __device__ __forceinline__ float wave_sum(float v) {
; #pragma unroll
;     for (int o = 1; o < 64; o <<= 1) v += __shfl_xor(v, o);
;     return v;
; __device__ __forceinline__ void ew_phase(const Frame& F, const bf16_t* f, const float* gpost, float alpha, const float* hin, float* hout, const float* gpre, bf16_t* xn, ...
;     ...
;         const float rstd = alpha / sqrtf(wave_sum(s) * (1.f / DM) + RMS_EPS);
;         float s2 = 0.f; f32x4* ho = (f32x4*)(hout + (size_t)m * DM) + F.lane;
; #pragma unroll
;         for (int j = 0; j < 4; ++j) { hv[j] = hv[j] + fv[j] * rstd * gp[j]; if (out24) store24(h24 + (size_t)m * (DM * 3), F.lane + 64 * j, hv[j]); else ho[64 * j] = hv[j]; s2 += (hv[j].x * hv[j].x + hv[j].y * hv[j].y) + (hv[j].z * hv[j].z + hv[j].w * hv[j].w); }
	v_add_f32_e32 v0, v0, v62
	v_xor_b32_e32 v62, 2, v230
	v_cmp_lt_i32_e32 vcc, v62, v35
	s_nop 1
	v_cndmask_b32_e32 v62, v230, v62, vcc
	v_lshlrev_b32_e32 v62, 2, v62
	ds_bpermute_b32 v62, v62, v0
	s_waitcnt lgkmcnt(0)
	v_add_f32_e32 v0, v0, v62
	v_xor_b32_e32 v62, 4, v230
	v_cmp_lt_i32_e32 vcc, v62, v35
	s_nop 1
	v_cndmask_b32_e32 v62, v230, v62, vcc
	v_lshlrev_b32_e32 v62, 2, v62
	ds_bpermute_b32 v62, v62, v0
	s_waitcnt lgkmcnt(0)
	v_add_f32_e32 v0, v0, v62
	v_xor_b32_e32 v62, 8, v230
	v_cmp_lt_i32_e32 vcc, v62, v35
	s_nop 1
	v_cndmask_b32_e32 v62, v230, v62, vcc
	v_lshlrev_b32_e32 v62, 2, v62
	ds_bpermute_b32 v62, v62, v0
	s_waitcnt lgkmcnt(0)
	v_add_f32_e32 v0, v0, v62
	v_xor_b32_e32 v62, 16, v230
	v_cmp_lt_i32_e32 vcc, v62, v35
	s_nop 1
	v_cndmask_b32_e32 v62, v230, v62, vcc
	v_lshlrev_b32_e32 v62, 2, v62
	ds_bpermute_b32 v62, v62, v0
	s_waitcnt lgkmcnt(0)
	v_add_f32_e32 v0, v0, v62
	v_xor_b32_e32 v62, 32, v230
	v_cmp_lt_i32_e32 vcc, v62, v35
	s_nop 1
	v_cndmask_b32_e32 v35, v230, v62, vcc
	v_lshlrev_b32_e32 v35, 2, v35
	ds_bpermute_b32 v35, v35, v0
	s_waitcnt lgkmcnt(0)
	v_add_f32_e32 v0, v0, v35
	v_fmamk_f32 v0, v0, 0x3a800000, v225
	v_cmp_gt_f32_e32 vcc, s18, v0
	v_mul_f32_e32 v35, 0x4f800000, v0
	s_nop 0
	v_cndmask_b32_e32 v0, v0, v35, vcc
	v_sqrt_f32_e32 v35, v0
	s_nop 0
	v_add_u32_e32 v62, -1, v35
	v_fma_f32 v64, -v62, v35, v0
	v_cmp_ge_f32_e64 s[0:1], 0, v64
	v_add_u32_e32 v64, 1, v35
	s_nop 0
	v_cndmask_b32_e64 v62, v35, v62, s[0:1]
	v_fma_f32 v35, -v64, v35, v0
	v_cmp_lt_f32_e64 s[0:1], 0, v35
	s_nop 1
	v_cndmask_b32_e64 v35, v62, v64, s[0:1]
	v_mul_f32_e32 v62, 0x37800000, v35
	v_cndmask_b32_e32 v35, v35, v62, vcc
	v_cmp_class_f32_e32 vcc, v0, v226
	s_nop 1
	v_cndmask_b32_e32 v0, v35, v0, vcc
	v_div_scale_f32 v35, s[0:1], v0, v0, 0.5
	v_rcp_f32_e32 v62, v35
	s_lshl_b64 s[0:1], s[6:7], 12
	s_cmp_eq_u32 s3, 8
	v_fma_f32 v64, -v35, v62, 1.0
	v_fmac_f32_e32 v62, v64, v62
	v_div_scale_f32 v64, vcc, 0.5, v0, 0.5
	v_mul_f32_e32 v66, v64, v62
	v_fma_f32 v67, -v35, v66, v64
	v_fmac_f32_e32 v66, v67, v62
	v_fma_f32 v35, -v35, v66, v64
	v_div_fmas_f32 v35, v35, v62, v66
	v_div_fixup_f32 v0, v35, v0, 0.5
	v_pk_mul_f32 v[26:27], v[0:1], v[26:27] op_sel_hi:[0,1]
	v_pk_mul_f32 v[28:29], v[0:1], v[28:29] op_sel_hi:[0,1]
	v_lshl_add_u64 v[66:67], v[20:21], 0, s[0:1]
	v_pk_fma_f32 v[24:25], v[4:5], v[28:29], v[24:25]
	v_pk_fma_f32 v[22:23], v[2:3], v[26:27], v[22:23]
	global_store_dwordx4 v[66:67], v[22:25], off
	v_mov_b32_e32 v62, v65
	s_cselect_b64 s[0:1], -1, 0
	v_mov_b32_e32 v22, v46
	v_mov_b32_e32 v23, v44
	v_mov_b32_e32 v44, v47
	v_pk_mul_f32 v[22:23], v[0:1], v[22:23] op_sel_hi:[0,1]
	v_pk_mul_f32 v[24:25], v[0:1], v[44:45] op_sel_hi:[0,1]
	v_pk_fma_f32 v[24:25], v[8:9], v[24:25], v[32:33]
	v_pk_fma_f32 v[22:23], v[6:7], v[22:23], v[30:31]
	global_store_dwordx4 v[66:67], v[22:25], off offset:1024
	s_nop 1
	v_pk_mul_f32 v[22:23], v[0:1], v[52:53] op_sel_hi:[0,1]
	v_pk_mul_f32 v[24:25], v[0:1], v[54:55] op_sel_hi:[0,1]
	v_pk_fma_f32 v[24:25], v[12:13], v[24:25], v[50:51]
	v_pk_fma_f32 v[22:23], v[10:11], v[22:23], v[48:49]
	global_store_dwordx4 v[66:67], v[22:25], off offset:2048
	s_nop 1
	v_pk_mul_f32 v[22:23], v[62:63], v[0:1] op_sel_hi:[1,0]
	v_pk_mul_f32 v[24:25], v[60:61], v[0:1] op_sel_hi:[1,0]
	v_pk_fma_f32 v[22:23], v[14:15], v[22:23], v[56:57]
	v_pk_fma_f32 v[24:25], v[16:17], v[24:25], v[58:59]
	global_store_dwordx4 v[66:67], v[22:25], off offset:3072
	s_branch .LBB0_910
